# all innermost loop heads aligned to 64 B (29 labels): code-placement test 2
# baseline (speedup 1.0000x reference)
; #define LAS __attribute__((address_space(3)))
; __global__ void __launch_bounds__(256, 2) mega(Params p, int ph_lo, int ph_hi) {
;     ...
;     cg::grid_group grid = cg::this_grid();
;     if (threadIdx.x == 0) xb_words = make_uint4(0u, 0u, 0u, 0u);
;     __syncthreads();
;     KP kp0 = (KP)__builtin_amdgcn_kernarg_segment_ptr();
;     XcdBarrier xb = xcd_barrier_post((unsigned*)(kp0->ws + OFF_BAR), (volatile LAS unsigned*)&xb_words);
;     if (ph_hi > 100000) grid.sync();
.LBB0_12:
	s_or_b64 exec, exec, s[10:11]
	v_mov_b32_e32 v0, 0
	global_load_dword v2, v0, s[8:9] offset:32 sc1
	v_and_b32_e32 v1, 0xffff0000, v1
	s_waitcnt vmcnt(0)
	v_and_b32_e32 v2, 0xffff0000, v2
	v_cmp_eq_u32_e32 vcc, v2, v1
	s_and_b64 exec, exec, vcc
	s_cbranch_execz .LBB0_15
	s_mov_b64 s[10:11], 0
	.p2align	6

; __device__ __forceinline__ void phase_post(KP p, int l, unsigned char* smem) {
;     for (int t = blockIdx.x; t < 544; t += gridDim.x) {
;         pool_gemm_tile(t, (const bf16_t*)(p->ws + OFF_POOLED), (const bf16_t*)(p->ws + OFF_POOLT), p->in[I_POOLS] + l * 512,
;                        (bf16_t*)(p->ws + OFF_BO), (bf16_t*)smem);
.LBB0_63:
	s_andn2_b64 vcc, exec, s[12:13]
	s_cbranch_vccnz .LBB0_67
	s_add_u32 s11, s58, 0x1bfe0000
	s_addc_u32 s12, s59, 0
	s_load_dwordx2 s[18:19], s[16:17], 0xb8
	s_add_u32 s13, s58, 0x2ec0000
	v_readlane_b32 s14, v230, 25
	s_addc_u32 s39, s59, 0
	v_readlane_b32 s15, v230, 26
	s_lshl_b32 s14, s14, 9
	s_ashr_i32 s15, s14, 31
	s_lshl_b64 s[22:23], s[14:15], 2
	s_waitcnt lgkmcnt(0)
	s_add_u32 s18, s18, s22
	s_addc_u32 s19, s19, s23
	s_add_u32 s22, s58, 0x16260000
	s_addc_u32 s23, s59, 0
	s_mov_b32 s42, s74
	s_mov_b32 s43, 0x18000
	s_movk_i32 s28, 0x2000
	s_movk_i32 s46, 0x6000
	.p2align	6

; __device__ __forceinline__ int tidx() { int t = threadIdx.x; asm volatile("" : "+v"(t)); return t; }
; __device__ __forceinline__ void phase_post(KP p, int l, unsigned char* smem) {
;     ...
;     const int tid_ = tidx();
;     const int lane = tid_ & 63, wid = tid_ >> 6;
;     bf16_t* BO = (bf16_t*)(p->ws + OFF_BO);
;     const float* yraw = (const float*)(p->ws + OFF_Y);
;     const float* oraw = yraw + (size_t)NTOK * 512;
;     const bf16_t* Rv = (const bf16_t*)(p->ws + OFF_RV); const bf16_t* Rg = (const bf16_t*)(p->ws + OFF_RG);
;     const bf16_t* SZ = (const bf16_t*)(p->ws + OFF_SZ);
;     const float* Rc = (const float*)(p->ws + OFF_RC);
;     const int c0 = lane * 8;
;     float gw[8], gb[8], nw[8];
;     {
;         const float4 a = *(const float4*)(p->in[I_GNW] + l * 512 + c0), a2 = *(const float4*)(p->in[I_GNW] + l * 512 + c0 + 4);
;         const float4 bq = *(const float4*)(p->in[I_GNB] + l * 512 + c0), b2 = *(const float4*)(p->in[I_GNB] + l * 512 + c0 + 4);
;         const float4 n1 = *(const float4*)(p->in[I_NORMW] + l * 128 + (c0 & 127)), n2 = *(const float4*)(p->in[I_NORMW] + l * 128 + (c0 & 127) + 4);
;         gw[0] = a.x; gw[1] = a.y; gw[2] = a.z; gw[3] = a.w; gw[4] = a2.x; gw[5] = a2.y; gw[6] = a2.z; gw[7] = a2.w;
;         gb[0] = bq.x; gb[1] = bq.y; gb[2] = bq.z; gb[3] = bq.w; gb[4] = b2.x; gb[5] = b2.y; gb[6] = b2.z; gb[7] = b2.w;
;         nw[0] = n1.x; nw[1] = n1.y; nw[2] = n1.z; nw[3] = n1.w; nw[4] = n2.x; nw[5] = n2.y; nw[6] = n2.z; nw[7] = n2.w;
;     }
;     for (int R = blockIdx.x * 4 + wid; R < NTOK; R += gridDim.x * 4) {
.LBB0_67:
	v_mov_b32_e32 v26, v192
	v_readlane_b32 s2, v231, 26
	v_ashrrev_i32_e32 v0, 6, v26
	s_nop 0
	v_add_u32_e32 v46, s2, v0
	s_movk_i32 s2, 0x4400
	v_cmp_gt_i32_e32 vcc, s2, v46
	s_and_saveexec_b64 s[18:19], vcc
	s_brev_b32 s46, 60
	v_readlane_b32 s22, v231, 62
	s_mov_b32 s47, 0x3c800000
	s_movk_i32 s11, 0x43ff
	v_readlane_b32 s23, v231, 63
	s_cbranch_execz .LBB0_70
	s_mov_b32 s2, s22
	s_add_u32 s22, s58, 0xa320000
	s_addc_u32 s23, s59, 0
	s_add_u32 s24, s58, 0x236e0000
	s_addc_u32 s25, s59, 0
	s_load_dwordx4 s[48:51], s[16:17], 0xa0
	s_load_dwordx2 s[12:13], s[16:17], 0xd8
	s_add_u32 s42, s58, 0x247e0000
	s_addc_u32 s43, s59, 0
	s_add_u32 s44, s58, 0x28cf3a00
	s_addc_u32 s45, s59, 0
	s_lshl_b64 s[14:15], s[14:15], 2
	s_waitcnt lgkmcnt(0)
	s_add_u32 s40, s48, s14
	s_addc_u32 s41, s49, s15
	v_and_b32_e32 v28, 63, v26
	s_add_u32 s14, s50, s14
	v_lshlrev_b32_e32 v12, 5, v28
	s_addc_u32 s15, s51, s15
	global_load_dwordx4 v[0:3], v12, s[40:41] offset:16
	global_load_dwordx4 v[4:7], v12, s[40:41]
	global_load_dwordx4 v[8:11], v12, s[14:15] offset:16
	global_load_dwordx4 v[14:17], v12, s[14:15]
	v_readlane_b32 s14, v230, 25
	v_readlane_b32 s15, v230, 26
	s_lshl_b32 s14, s14, 7
	s_ashr_i32 s15, s14, 31
	s_lshl_b64 s[14:15], s[14:15], 2
	s_add_u32 s12, s12, s14
	v_lshlrev_b32_e32 v12, 5, v26
	s_addc_u32 s13, s13, s15
	v_and_b32_e32 v12, 0x1e0, v12
	global_load_dwordx4 v[18:21], v12, s[12:13] offset:16
	global_load_dwordx4 v[22:25], v12, s[12:13]
	v_lshrrev_b32_e32 v26, 1, v26
	v_and_b32_e32 v26, 28, v26
	v_mov_b32_e32 v27, v13
	v_lshl_add_u64 v[26:27], s[58:59], 0, v[26:27]
	s_mov_b64 s[12:13], 0x258e0000
	v_lshl_add_u64 v[48:49], v[26:27], 0, s[12:13]
	v_lshlrev_b32_e32 v26, 4, v28
	v_mov_b32_e32 v27, v13
	v_lshl_add_u64 v[26:27], s[58:59], 0, v[26:27]
	s_mov_b64 s[12:13], 0x16260000
	v_lshlrev_b32_e32 v12, 3, v28
	v_lshl_add_u64 v[50:51], v[26:27], 0, s[12:13]
	s_mov_b64 s[14:15], 0
	.p2align	6

; __device__ __forceinline__ void phase_merge(const bf16_t* G, const bf16_t* BO, const bf16_t* Wb, bf16_t* M, bf16_t* sm) {
;     ...
;     for (int t = blockIdx.x; t < 136 * 16; t += gridDim.x) {
;         const int tm = t >> 4, tn = t & 15;
;     ...
;         for (int mt = 0; mt < 4; ++mt) {
;             const int row = tm * 128 + wr * 64 + mt * 16 + fr;
;             float v[8]; gather_cols<2>(accm, mt, v);
;             u32x4 o;
; #pragma unroll
;             for (int q = 0; q < 4; ++q) o[q] = pack2(v[2 * q], v[2 * q + 1]);
;             *(u32x4*)(M + (size_t)row * 1024 + cbase) = o;
;         }
;     }
.LBB0_346:
	s_or_b64 exec, exec, s[12:13]
	v_readlane_b32 s12, v231, 62
	s_add_i32 s86, s86, s62
	s_add_i32 s11, s11, s12
	s_cmpk_gt_i32 s86, 0x87f
	s_waitcnt lgkmcnt(0)
	s_barrier
	v_readlane_b32 s13, v231, 63
	s_cbranch_scc1 .LBB0_421
	.p2align	6

; __device__ __forceinline__ float4 ldnt4(const float* p) { const f32x4 v = __builtin_nontemporal_load((const f32x4*)p); return make_float4(v[0], v[1], v[2], v[3]); }
; __device__ __forceinline__ void phase_ln(const float* Y, float* X, bf16_t* xb, const float* g, const float* b) {
;     ...
;     for (; row < NTOK; row += stride) {
;         const int nrow = row + stride;
;         if (nrow < NTOK) {
; #pragma unroll
;             for (int i = 0; i < 4; ++i) vn[i] = ldnt4(Y + (size_t)nrow * 1024 + (lane + 64 * i) * 4);
;         }
;         float s = 0.f;
; #pragma unroll
;         for (int i = 0; i < 4; ++i) s += v[i].x + v[i].y + v[i].z + v[i].w;
;         const float mean = wave_sum(s) * (1.f / 1024.f);
;         float q = 0.f;
; #pragma unroll
;         for (int i = 0; i < 4; ++i) {
;             v[i].x -= mean; v[i].y -= mean; v[i].z -= mean; v[i].w -= mean;
;             q += v[i].x * v[i].x + v[i].y * v[i].y + v[i].z * v[i].z + v[i].w * v[i].w;
;         }
;         const float rstd = rsqrtf(wave_sum(q) * (1.f / 1024.f) + 1e-5f);
; #pragma unroll
;         for (int i = 0; i < 4; ++i) {
;             const int c4 = lane + 64 * i;
;             float4 o;
;             o.x = v[i].x * rstd * gg[i].x + bb[i].x; o.y = v[i].y * rstd * gg[i].y + bb[i].y;
;             o.z = v[i].z * rstd * gg[i].z + bb[i].z; o.w = v[i].w * rstd * gg[i].w + bb[i].w;
;             ((float4*)(X + (size_t)row * 1024))[c4] = o;
;             ((uint2*)(xb + (size_t)row * 1024))[c4] = make_uint2(pack2(o.x, o.y), pack2(o.z, o.w));
;         }
; #pragma unroll
;         for (int i = 0; i < 4; ++i) v[i] = vn[i];
;     }
.LBB0_485:
	s_or_b64 exec, exec, s[22:23]
	s_waitcnt vmcnt(11)
	v_mov_b32_e32 v76, v30
	s_waitcnt vmcnt(10)
	v_mov_b32_e32 v77, v42
	v_mov_b32_e32 v78, v31
	v_mov_b32_e32 v79, v43
	v_pk_add_f32 v[76:77], v[76:77], v[78:79]
	v_mov_b32_e32 v78, v32
	v_mov_b32_e32 v79, v44
	v_pk_add_f32 v[76:77], v[76:77], v[78:79]
	v_mov_b32_e32 v78, v33
	v_mov_b32_e32 v79, v45
	v_pk_add_f32 v[76:77], v[76:77], v[78:79]
	s_waitcnt vmcnt(9)
	v_mov_b32_e32 v78, v39
	v_add_f32_e32 v69, 0, v76
	v_add_f32_e32 v69, v69, v77
	v_mov_b32_e32 v76, v38
	s_waitcnt vmcnt(8)
	v_mov_b32_e32 v77, v46
	v_mov_b32_e32 v79, v47
	v_pk_add_f32 v[76:77], v[76:77], v[78:79]
	v_mov_b32_e32 v78, v40
	v_mov_b32_e32 v79, v48
	v_pk_add_f32 v[76:77], v[76:77], v[78:79]
	v_mov_b32_e32 v78, v41
	v_mov_b32_e32 v79, v49
	v_pk_add_f32 v[76:77], v[76:77], v[78:79]
	v_lshl_add_u64 v[78:79], s[58:59], 0, v[70:71]
	v_add_f32_e32 v69, v69, v76
	v_add_f32_e32 v69, v69, v77
	s_and_b64 s[12:13], exec, s[40:41]
	s_or_b64 s[18:19], s[12:13], s[18:19]
	v_add_f32_dpp v69, v69, v69 quad_perm:[1,0,3,2] row_mask:0xf bank_mask:0xf bound_ctrl:1
	v_lshl_add_u64 v[70:71], v[70:71], 0, s[44:45]
	v_lshl_add_u64 v[74:75], v[74:75], 0, s[46:47]
	v_add_f32_dpp v69, v69, v69 quad_perm:[2,3,0,1] row_mask:0xf bank_mask:0xf bound_ctrl:1
	s_nop 1
	v_add_f32_dpp v69, v69, v69 row_half_mirror row_mask:0xf bank_mask:0xf bound_ctrl:1
	s_nop 1
	v_add_f32_dpp v69, v69, v69 row_mirror row_mask:0xf bank_mask:0xf bound_ctrl:1
	ds_bpermute_b32 v76, v12, v69
	s_waitcnt lgkmcnt(0)
	v_add_f32_e32 v69, v69, v76
	ds_bpermute_b32 v76, v67, v69
	s_waitcnt lgkmcnt(0)
	v_add_f32_e32 v69, v69, v76
	v_mul_f32_e32 v76, 0x3a800000, v69
	v_pk_add_f32 v[30:31], v[30:31], v[76:77] op_sel_hi:[1,0] neg_lo:[0,1] neg_hi:[0,1]
	v_pk_add_f32 v[42:43], v[42:43], v[76:77] op_sel_hi:[1,0] neg_lo:[0,1] neg_hi:[0,1]
	v_mov_b32_e32 v82, v31
	v_mov_b32_e32 v83, v43
	v_pk_add_f32 v[32:33], v[32:33], v[76:77] op_sel_hi:[1,0] neg_lo:[0,1] neg_hi:[0,1]
	v_pk_add_f32 v[44:45], v[44:45], v[76:77] op_sel_hi:[1,0] neg_lo:[0,1] neg_hi:[0,1]
	v_mov_b32_e32 v80, v30
	v_mov_b32_e32 v81, v42
	v_pk_mul_f32 v[82:83], v[82:83], v[82:83]
	v_pk_add_f32 v[38:39], v[38:39], v[76:77] op_sel_hi:[1,0] neg_lo:[0,1] neg_hi:[0,1]
	v_pk_fma_f32 v[80:81], v[80:81], v[80:81], v[82:83]
	v_mov_b32_e32 v82, v32
	v_mov_b32_e32 v83, v44
	v_pk_add_f32 v[46:47], v[46:47], v[76:77] op_sel_hi:[1,0] neg_lo:[0,1] neg_hi:[0,1]
	v_pk_fma_f32 v[80:81], v[82:83], v[82:83], v[80:81]
	v_mov_b32_e32 v82, v47
	v_mov_b32_e32 v83, v39
	v_pk_add_f32 v[40:41], v[40:41], v[76:77] op_sel_hi:[1,0] neg_lo:[0,1] neg_hi:[0,1]
	v_pk_add_f32 v[48:49], v[48:49], v[76:77] op_sel_hi:[1,0] neg_lo:[0,1] neg_hi:[0,1]
	v_mov_b32_e32 v76, v46
	v_mov_b32_e32 v77, v38
	v_pk_mul_f32 v[82:83], v[82:83], v[82:83]
	v_mov_b32_e32 v84, v33
	v_mov_b32_e32 v85, v45
	v_pk_fma_f32 v[76:77], v[76:77], v[76:77], v[82:83]
	v_mov_b32_e32 v82, v48
	v_mov_b32_e32 v83, v40
	v_pk_fma_f32 v[80:81], v[84:85], v[84:85], v[80:81]
	v_mov_b32_e32 v84, v49
	v_mov_b32_e32 v85, v41
	v_pk_fma_f32 v[76:77], v[82:83], v[82:83], v[76:77]
	v_add_f32_e32 v69, v80, v81
	v_pk_fma_f32 v[76:77], v[84:85], v[84:85], v[76:77]
	s_nop 0
	v_add_f32_e32 v69, v77, v69
	v_add_f32_e32 v69, v76, v69
	s_nop 1
	v_add_f32_dpp v69, v69, v69 quad_perm:[1,0,3,2] row_mask:0xf bank_mask:0xf bound_ctrl:1
	s_nop 1
	v_add_f32_dpp v69, v69, v69 quad_perm:[2,3,0,1] row_mask:0xf bank_mask:0xf bound_ctrl:1
	s_nop 1
	v_add_f32_dpp v69, v69, v69 row_half_mirror row_mask:0xf bank_mask:0xf bound_ctrl:1
	s_nop 1
	v_add_f32_dpp v69, v69, v69 row_mirror row_mask:0xf bank_mask:0xf bound_ctrl:1
	ds_bpermute_b32 v76, v12, v69
	s_waitcnt lgkmcnt(0)
	v_add_f32_e32 v69, v69, v76
	ds_bpermute_b32 v76, v67, v69
	s_waitcnt lgkmcnt(0)
	v_add_f32_e32 v69, v69, v76
	v_fmamk_f32 v69, v69, 0x3a800000, v194
	v_cmp_gt_f32_e32 vcc, s63, v69
	v_mul_f32_e32 v76, 0x4b800000, v69
	s_nop 0
	v_cndmask_b32_e32 v69, v69, v76, vcc
	v_rsq_f32_e32 v69, v69
	s_nop 0
	v_mul_f32_e32 v76, 0x45800000, v69
	v_cndmask_b32_e32 v76, v69, v76, vcc
	v_pk_mul_f32 v[30:31], v[30:31], v[76:77] op_sel_hi:[1,0]
	v_pk_mul_f32 v[32:33], v[32:33], v[76:77] op_sel_hi:[1,0]
	s_waitcnt vmcnt(5)
	v_pk_fma_f32 v[30:31], v[0:1], v[30:31], v[8:9]
	v_pk_fma_f32 v[32:33], v[2:3], v[32:33], v[10:11]
	v_add_co_u32_e32 v78, vcc, s0, v78
	global_store_dwordx4 v[72:73], v[30:33], off
	s_nop 0
	v_addc_co_u32_e32 v79, vcc, 0, v79, vcc
	v_cvt_pk_bf16_f32 v30, v30, v31
	v_cvt_pk_bf16_f32 v31, v32, v33
	global_store_dwordx2 v[78:79], v[30:31], off
	v_pk_mul_f32 v[30:31], v[42:43], v[76:77] op_sel_hi:[1,0]
	v_pk_mul_f32 v[32:33], v[44:45], v[76:77] op_sel_hi:[1,0]
	s_waitcnt vmcnt(6)
	v_pk_fma_f32 v[30:31], v[4:5], v[30:31], v[14:15]
	v_pk_fma_f32 v[32:33], v[6:7], v[32:33], v[16:17]
	global_store_dwordx4 v[72:73], v[30:33], off offset:1024
	s_waitcnt vmcnt(5)
	v_mov_b32_e32 v42, v54
	v_mov_b32_e32 v43, v55
	v_cvt_pk_bf16_f32 v30, v30, v31
	v_cvt_pk_bf16_f32 v31, v32, v33
	global_store_dwordx2 v[78:79], v[30:31], off offset:512
	v_pk_mul_f32 v[30:31], v[38:39], v[76:77] op_sel_hi:[1,0]
	v_pk_mul_f32 v[32:33], v[40:41], v[76:77] op_sel_hi:[1,0]
	s_waitcnt vmcnt(5)
	v_pk_fma_f32 v[30:31], v[18:19], v[30:31], v[26:27]
	v_pk_fma_f32 v[32:33], v[20:21], v[32:33], v[28:29]
	global_store_dwordx4 v[72:73], v[30:33], off offset:2048
	v_mov_b32_e32 v44, v56
	v_mov_b32_e32 v45, v57
	v_cvt_pk_bf16_f32 v30, v30, v31
	v_cvt_pk_bf16_f32 v31, v32, v33
	global_store_dwordx2 v[78:79], v[30:31], off offset:1024
	v_pk_mul_f32 v[30:31], v[46:47], v[76:77] op_sel_hi:[1,0]
	v_pk_mul_f32 v[32:33], v[48:49], v[76:77] op_sel_hi:[1,0]
	s_waitcnt vmcnt(6)
	v_pk_fma_f32 v[30:31], v[22:23], v[30:31], v[34:35]
	v_pk_fma_f32 v[32:33], v[24:25], v[32:33], v[36:37]
	global_store_dwordx4 v[72:73], v[30:33], off offset:3072
	v_lshl_add_u64 v[72:73], v[72:73], 0, s[46:47]
	v_mov_b32_e32 v38, v58
	v_cvt_pk_bf16_f32 v30, v30, v31
	v_cvt_pk_bf16_f32 v31, v32, v33
	global_store_dwordx2 v[78:79], v[30:31], off offset:1536
	v_mov_b32_e32 v30, v50
	v_mov_b32_e32 v31, v51
	v_mov_b32_e32 v32, v52
	v_mov_b32_e32 v33, v53
	v_mov_b32_e32 v39, v59
	v_mov_b32_e32 v40, v60
	v_mov_b32_e32 v41, v61
	v_mov_b32_e32 v46, v62
	v_mov_b32_e32 v47, v63
	v_mov_b32_e32 v48, v64
	v_mov_b32_e32 v49, v65
	s_andn2_b64 exec, exec, s[18:19]
	s_cbranch_execz .LBB0_488
	.p2align	6

; __device__ __forceinline__ int tidx() { int t = threadIdx.x; asm volatile("" : "+v"(t)); return t; }
; __device__ __forceinline__ void conv_sample_kv(KP p, int l) {
;     const int tid_ = tidx();
;     const size_t gt = (size_t)blockIdx.x * 256 + tid_, gs = (size_t)gridDim.x * 256;
;     const float* ck = p->in[I_CMK] + (size_t)l * 128 * 256 * 256;
;     const float* cv = p->in[I_CMV] + (size_t)l * 128 * 256 * 256;
;     bf16_t* Ks = (bf16_t*)(p->ws + OFF_KS); bf16_t* Vts = (bf16_t*)(p->ws + OFF_VTS);
;     for (size_t i0 = gt; i0 < (size_t)128 * 256 * 64; i0 += 4 * gs) {
.LBB0_489:
	v_readlane_b32 s82, v230, 21
	v_readlane_b32 s83, v230, 22
	v_readlane_b32 s84, v231, 14
	v_readlane_b32 s90, v231, 34
	s_and_b64 vcc, exec, s[14:15]
	v_readlane_b32 s75, v233, 29
	v_readlane_b32 s83, v233, 30
	v_readlane_b32 s85, v231, 15
	v_readlane_b32 s91, v231, 35
	s_movk_i32 s28, 0x7f00
	s_cbranch_vccz .LBB0_1475
	v_readlane_b32 s12, v230, 27
	v_readlane_b32 s13, v230, 28
	s_andn2_b64 vcc, exec, s[12:13]
	s_cbranch_vccnz .LBB0_521
	v_and_b32_e32 v242, 15, v192
	v_lshrrev_b32_e32 v243, 4, v192
	v_lshlrev_b32_e32 v236, 4, v242
	v_lshl_add_u32 v238, v243, 12, v236
	v_lshl_add_u32 v236, v243, 10, v236
	v_lshlrev_b32_e32 v237, 3, v242
	v_lshl_add_u32 v237, v243, 7, v237
	v_mul_u32_u24_e32 v239, 0x840, v242
	v_lshl_add_u32 v239, v243, 3, v239
	v_and_b32_e32 v242, 31, v192
	v_lshrrev_b32_e32 v243, 5, v192
	v_lshlrev_b32_e32 v241, 4, v242
	v_mul_u32_u24_e32 v240, 0x210, v243
	v_add_u32_e32 v240, v240, v241
	v_lshl_add_u32 v241, v243, 9, v241
	s_load_dwordx4 s[44:47], s[16:17], 0x18
	v_readlane_b32 s12, v230, 25
	v_readlane_b32 s24, v231, 56
	s_nop 1
	v_writelane_b32 v230, s12, 25
	v_writelane_b32 v230, s3, 26
	s_ashr_i32 s13, s12, 31
	s_lshl_b64 s[22:23], s[12:13], 25
	s_waitcnt lgkmcnt(0)
	s_add_u32 s44, s44, s22
	s_addc_u32 s45, s45, s23
	s_add_u32 s46, s46, s22
	s_addc_u32 s47, s47, s23
	s_cmpk_lt_u32 s24, 0x200
	s_cbranch_scc0 .Lconv_done
	.p2align	6

; __device__ __forceinline__ float4 ldnt4(const float* p) { const f32x4 v = __builtin_nontemporal_load((const f32x4*)p); return make_float4(v[0], v[1], v[2], v[3]); }
; __device__ __forceinline__ void phase_init(KP p, float* tile) {
;     ...
;         for (size_t i0 = gt; i0 < n4; i0 += 4 * gs) {
;             float4 v[4];
; #pragma unroll
;             for (int u = 0; u < 4; ++u) { const size_t i = i0 + u * gs; if (i < n4) v[u] = i < np4 ? ldnt4((const float*)(xp + i)) : ldnt4((const float*)(xs + (i - np4))); }
; #pragma unroll
;             for (int u = 0; u < 4; ++u) { const size_t i = i0 + u * gs; if (i < n4) { X[i] = v[u]; xb[i] = make_uint2(pack2(v[u].x, v[u].y), pack2(v[u].z, v[u].w)); } }
;         }
.LBB0_599:
	s_or_b64 exec, exec, s[40:41]
	s_add_u32 s2, s14, s14
	s_addc_u32 s11, s15, s15
	s_add_u32 s12, s2, s14
	s_addc_u32 s13, s11, s15
	v_lshl_add_u64 v[56:57], s[12:13], 0, v[54:55]
	s_add_u32 s52, s52, s24
	s_mov_b64 s[12:13], 0x43ffff
	s_addc_u32 s53, s53, s25
	v_cmp_lt_u64_e32 vcc, s[12:13], v[56:57]
	v_lshl_add_u64 v[22:23], v[22:23], 0, s[22:23]
	v_lshl_add_u64 v[24:25], v[24:25], 0, s[22:23]
	v_lshl_add_u64 v[38:39], v[38:39], 0, s[22:23]
	s_or_b64 s[50:51], vcc, s[50:51]
	v_lshl_add_u64 v[48:49], v[48:49], 0, s[22:23]
	s_andn2_b64 exec, exec, s[50:51]
	s_cbranch_execz .LBB0_612
	.p2align	6

; __device__ __forceinline__ void phase_init(KP p, float* tile) {
;     ...
;     {
;         const float4* mp = (const float4*)p->in[I_MEMP]; uint2* mb = (uint2*)(ws + OFF_MEMB);
;         for (size_t i = gt; i < (size_t)2048 * 256; i += gs) { float4 v = mp[i]; mb[i] = make_uint2(pack2(v.x, v.y), pack2(v.z, v.w)); }
.LBB0_612:
	s_or_b64 exec, exec, s[18:19]
	s_mov_b64 s[12:13], 0x80000
	v_cmp_gt_u64_e32 vcc, s[12:13], v[20:21]
	s_and_saveexec_b64 s[18:19], vcc
	s_cbranch_execz .LBB0_615
	s_load_dwordx2 s[12:13], s[16:17], 0x10
	v_readlane_b32 s2, v231, 48
	s_add_u32 s22, s58, s2
	v_readlane_b32 s2, v231, 51
	s_addc_u32 s23, s59, s2
	s_waitcnt vmcnt(0)
	v_lshl_add_u64 v[0:1], v[18:19], 3, s[22:23]
	s_lshl_b64 s[22:23], s[86:87], 11
	v_readlane_b32 s2, v231, 52
	s_waitcnt lgkmcnt(0)
	s_add_u32 s12, s12, s2
	v_readlane_b32 s2, v231, 55
	s_addc_u32 s13, s13, s2
	v_lshl_add_u64 v[2:3], v[18:19], 4, s[12:13]
	s_lshl_b64 s[24:25], s[86:87], 12
	s_mov_b64 s[40:41], 0
	.p2align	6

; __device__ __forceinline__ float ldnt(const float* p) { return __builtin_nontemporal_load(p); }
; __device__ __forceinline__ void conv_job(const float* __restrict__ src, int ld, int K, bf16_t* dst, int Ndst, int kind, float* tile) {
;     ...
;         const int tk = t % tilesK, tn = t / tilesK, k0 = tk << 6, n0 = tn << 6;
; #pragma unroll
;         for (int i = 0; i < 16; ++i) tile[(ty + 4 * i) * 65 + tx] = r[i];
;         __syncthreads();
;         const int tnext = t + gridDim.x;
;         if (tnext < ntiles) {
;             const int tk2 = tnext % tilesK, tn2 = tnext / tilesK, k2 = tk2 << 6, n2 = tn2 << 6;
;             const int sc = mapcol(kind, n2 + tx);
; #pragma unroll
;             for (int i = 0; i < 16; ++i) r[i] = sc >= 0 ? ldnt(src + (size_t)(k2 + ty + 4 * i) * ld + sc) : 0.f;
;         }
; #pragma unroll
;         for (int i = 0; i < 8; ++i) {
;             const int nn = ty2 + 8 * i;
;             *(unsigned*)(dst + (size_t)(n0 + nn) * K + k0 + 2 * tx2) = pack2(tile[(2 * tx2) * 65 + nn], tile[(2 * tx2 + 1) * 65 + nn]);
;         }
;         __syncthreads();
.LBB0_654:
	s_ashr_i32 s12, s23, 31
	s_lshr_b32 s12, s12, 28
	s_add_i32 s12, s23, s12
	s_ashr_i32 s23, s12, 4
	ds_read2_b32 v[28:29], v25 offset0:65 offset1:73
	ds_read2_b32 v[30:31], v25 offset1:8
	s_lshl_b32 s12, s23, 10
	s_sub_i32 s12, s11, s12
	v_lshl_add_u32 v32, s23, 6, v24
	s_ashr_i32 s13, s12, 31
	v_ashrrev_i32_e32 v33, 31, v32
	v_lshl_add_u64 v[20:21], s[12:13], 1, v[18:19]
	v_lshlrev_b64 v[34:35], 11, v[32:33]
	s_waitcnt lgkmcnt(0)
	v_cvt_pk_bf16_f32 v16, v30, v28
	v_lshl_add_u64 v[34:35], v[20:21], 0, v[34:35]
	v_add_u32_e32 v28, 8, v32
	global_store_dword v[34:35], v16, off
	v_cvt_pk_bf16_f32 v16, v31, v29
	v_ashrrev_i32_e32 v29, 31, v28
	v_lshlrev_b64 v[28:29], 11, v[28:29]
	v_lshl_add_u64 v[28:29], v[20:21], 0, v[28:29]
	global_store_dword v[28:29], v16, off
	ds_read2_b32 v[28:29], v25 offset0:16 offset1:24
	ds_read2_b32 v[30:31], v25 offset0:81 offset1:89
	v_add_u32_e32 v34, 16, v32
	v_ashrrev_i32_e32 v35, 31, v34
	v_lshlrev_b64 v[34:35], 11, v[34:35]
	v_lshl_add_u64 v[34:35], v[20:21], 0, v[34:35]
	s_waitcnt lgkmcnt(0)
	v_cvt_pk_bf16_f32 v16, v28, v30
	v_add_u32_e32 v28, 24, v32
	global_store_dword v[34:35], v16, off
	v_cvt_pk_bf16_f32 v16, v29, v31
	v_ashrrev_i32_e32 v29, 31, v28
	v_lshlrev_b64 v[28:29], 11, v[28:29]
	v_lshl_add_u64 v[28:29], v[20:21], 0, v[28:29]
	global_store_dword v[28:29], v16, off
	ds_read2_b32 v[28:29], v25 offset0:32 offset1:40
	ds_read2_b32 v[30:31], v25 offset0:97 offset1:105
	v_add_u32_e32 v34, 32, v32
	v_ashrrev_i32_e32 v35, 31, v34
	v_lshlrev_b64 v[34:35], 11, v[34:35]
	v_lshl_add_u64 v[34:35], v[20:21], 0, v[34:35]
	s_waitcnt lgkmcnt(0)
	v_cvt_pk_bf16_f32 v16, v28, v30
	v_add_u32_e32 v28, 40, v32
	global_store_dword v[34:35], v16, off
	v_cvt_pk_bf16_f32 v16, v29, v31
	v_ashrrev_i32_e32 v29, 31, v28
	v_lshlrev_b64 v[28:29], 11, v[28:29]
	v_lshl_add_u64 v[28:29], v[20:21], 0, v[28:29]
	global_store_dword v[28:29], v16, off
	ds_read2_b32 v[28:29], v25 offset0:113 offset1:121
	ds_read2_b32 v[30:31], v25 offset0:48 offset1:56
	v_add_u32_e32 v34, 48, v32
	v_ashrrev_i32_e32 v35, 31, v34
	v_lshlrev_b64 v[34:35], 11, v[34:35]
	v_lshl_add_u64 v[34:35], v[20:21], 0, v[34:35]
	s_waitcnt lgkmcnt(0)
	v_cvt_pk_bf16_f32 v16, v30, v28
	v_add_u32_e32 v28, 56, v32
	global_store_dword v[34:35], v16, off
	v_cvt_pk_bf16_f32 v16, v31, v29
	v_ashrrev_i32_e32 v29, 31, v28
	v_lshlrev_b64 v[28:29], 11, v[28:29]
	v_lshl_add_u64 v[20:21], v[20:21], 0, v[28:29]
	s_add_i32 s11, s11, s2
	s_andn2_b64 vcc, exec, s[18:19]
	s_mov_b32 s23, s22
	global_store_dword v[20:21], v16, off
	s_barrier
	s_cbranch_vccz .LBB0_688
	.p2align	6

; __device__ __forceinline__ float ldnt(const float* p) { return __builtin_nontemporal_load(p); }
; __device__ __forceinline__ void conv_job(const float* __restrict__ src, int ld, int K, bf16_t* dst, int Ndst, int kind, float* tile) {
;     ...
;         const int tk = t % tilesK, tn = t / tilesK, k0 = tk << 6, n0 = tn << 6;
; #pragma unroll
;         for (int i = 0; i < 16; ++i) tile[(ty + 4 * i) * 65 + tx] = r[i];
;         __syncthreads();
;         const int tnext = t + gridDim.x;
;         if (tnext < ntiles) {
;             const int tk2 = tnext % tilesK, tn2 = tnext / tilesK, k2 = tk2 << 6, n2 = tn2 << 6;
;             const int sc = mapcol(kind, n2 + tx);
; #pragma unroll
;             for (int i = 0; i < 16; ++i) r[i] = sc >= 0 ? ldnt(src + (size_t)(k2 + ty + 4 * i) * ld + sc) : 0.f;
;         }
; #pragma unroll
;         for (int i = 0; i < 8; ++i) {
;             const int nn = ty2 + 8 * i;
;             *(unsigned*)(dst + (size_t)(n0 + nn) * K + k0 + 2 * tx2) = pack2(tile[(2 * tx2) * 65 + nn], tile[(2 * tx2 + 1) * 65 + nn]);
;         }
;         __syncthreads();
.LBB0_724:
	s_ashr_i32 s24, s13, 31
	s_lshr_b32 s24, s24, 27
	s_add_i32 s13, s13, s24
	s_ashr_i32 s13, s13, 5
	ds_read2_b32 v[28:29], v24 offset0:65 offset1:73
	ds_read2_b32 v[30:31], v24 offset1:8
	s_lshl_b32 s24, s13, 11
	s_sub_i32 s24, s11, s24
	v_lshl_add_u32 v32, s13, 6, v23
	s_ashr_i32 s25, s24, 31
	v_ashrrev_i32_e32 v33, 31, v32
	v_lshl_add_u64 v[20:21], s[24:25], 1, v[18:19]
	v_lshlrev_b64 v[34:35], 12, v[32:33]
	s_waitcnt lgkmcnt(0)
	v_cvt_pk_bf16_f32 v16, v30, v28
	v_lshl_add_u64 v[34:35], v[20:21], 0, v[34:35]
	v_add_u32_e32 v28, 8, v32
	global_store_dword v[34:35], v16, off
	v_cvt_pk_bf16_f32 v16, v31, v29
	v_ashrrev_i32_e32 v29, 31, v28
	v_lshlrev_b64 v[28:29], 12, v[28:29]
	v_lshl_add_u64 v[28:29], v[20:21], 0, v[28:29]
	global_store_dword v[28:29], v16, off
	ds_read2_b32 v[28:29], v24 offset0:16 offset1:24
	ds_read2_b32 v[30:31], v24 offset0:81 offset1:89
	v_add_u32_e32 v34, 16, v32
	v_ashrrev_i32_e32 v35, 31, v34
	v_lshlrev_b64 v[34:35], 12, v[34:35]
	v_lshl_add_u64 v[34:35], v[20:21], 0, v[34:35]
	s_waitcnt lgkmcnt(0)
	v_cvt_pk_bf16_f32 v16, v28, v30
	v_add_u32_e32 v28, 24, v32
	global_store_dword v[34:35], v16, off
	v_cvt_pk_bf16_f32 v16, v29, v31
	v_ashrrev_i32_e32 v29, 31, v28
	v_lshlrev_b64 v[28:29], 12, v[28:29]
	v_lshl_add_u64 v[28:29], v[20:21], 0, v[28:29]
	global_store_dword v[28:29], v16, off
	ds_read2_b32 v[28:29], v24 offset0:32 offset1:40
	ds_read2_b32 v[30:31], v24 offset0:97 offset1:105
	v_add_u32_e32 v34, 32, v32
	v_ashrrev_i32_e32 v35, 31, v34
	v_lshlrev_b64 v[34:35], 12, v[34:35]
	v_lshl_add_u64 v[34:35], v[20:21], 0, v[34:35]
	s_waitcnt lgkmcnt(0)
	v_cvt_pk_bf16_f32 v16, v28, v30
	v_add_u32_e32 v28, 40, v32
	global_store_dword v[34:35], v16, off
	v_cvt_pk_bf16_f32 v16, v29, v31
	v_ashrrev_i32_e32 v29, 31, v28
	v_lshlrev_b64 v[28:29], 12, v[28:29]
	v_lshl_add_u64 v[28:29], v[20:21], 0, v[28:29]
	global_store_dword v[28:29], v16, off
	ds_read2_b32 v[28:29], v24 offset0:113 offset1:121
	ds_read2_b32 v[30:31], v24 offset0:48 offset1:56
	v_add_u32_e32 v34, 48, v32
	v_ashrrev_i32_e32 v35, 31, v34
	v_lshlrev_b64 v[34:35], 12, v[34:35]
	v_lshl_add_u64 v[34:35], v[20:21], 0, v[34:35]
	s_waitcnt lgkmcnt(0)
	v_cvt_pk_bf16_f32 v16, v30, v28
	v_add_u32_e32 v28, 56, v32
	global_store_dword v[34:35], v16, off
	v_cvt_pk_bf16_f32 v16, v31, v29
	v_ashrrev_i32_e32 v29, 31, v28
	v_lshlrev_b64 v[28:29], 12, v[28:29]
	v_lshl_add_u64 v[20:21], v[20:21], 0, v[28:29]
	s_add_i32 s11, s11, s2
	s_andn2_b64 vcc, exec, s[22:23]
	s_mov_b32 s13, s12
	global_store_dword v[20:21], v16, off
	s_barrier
	s_cbranch_vccz .LBB0_758
	.p2align	6

; __device__ __forceinline__ float ldnt(const float* p) { return __builtin_nontemporal_load(p); }
; __device__ __forceinline__ void conv_job(const float* __restrict__ src, int ld, int K, bf16_t* dst, int Ndst, int kind, float* tile) {
;     ...
;         const int tk = t % tilesK, tn = t / tilesK, k0 = tk << 6, n0 = tn << 6;
; #pragma unroll
;         for (int i = 0; i < 16; ++i) tile[(ty + 4 * i) * 65 + tx] = r[i];
;         __syncthreads();
;         const int tnext = t + gridDim.x;
;         if (tnext < ntiles) {
;             const int tk2 = tnext % tilesK, tn2 = tnext / tilesK, k2 = tk2 << 6, n2 = tn2 << 6;
;             const int sc = mapcol(kind, n2 + tx);
; #pragma unroll
;             for (int i = 0; i < 16; ++i) r[i] = sc >= 0 ? ldnt(src + (size_t)(k2 + ty + 4 * i) * ld + sc) : 0.f;
;         }
; #pragma unroll
;         for (int i = 0; i < 8; ++i) {
;             const int nn = ty2 + 8 * i;
;             *(unsigned*)(dst + (size_t)(n0 + nn) * K + k0 + 2 * tx2) = pack2(tile[(2 * tx2) * 65 + nn], tile[(2 * tx2 + 1) * 65 + nn]);
;         }
;         __syncthreads();
.LBB0_795:
	s_ashr_i32 s12, s25, 31
	s_lshr_b32 s12, s12, 28
	s_add_i32 s12, s25, s12
	s_ashr_i32 s25, s12, 4
	ds_read2_b32 v[28:29], v25 offset0:65 offset1:73
	ds_read2_b32 v[30:31], v25 offset1:8
	s_lshl_b32 s12, s25, 10
	s_sub_i32 s12, s11, s12
	v_lshl_add_u32 v32, s25, 6, v24
	s_ashr_i32 s13, s12, 31
	v_ashrrev_i32_e32 v33, 31, v32
	v_lshl_add_u64 v[20:21], s[12:13], 1, v[18:19]
	v_lshlrev_b64 v[34:35], 11, v[32:33]
	s_waitcnt lgkmcnt(0)
	v_cvt_pk_bf16_f32 v16, v30, v28
	v_lshl_add_u64 v[34:35], v[20:21], 0, v[34:35]
	v_add_u32_e32 v28, 8, v32
	global_store_dword v[34:35], v16, off
	v_cvt_pk_bf16_f32 v16, v31, v29
	v_ashrrev_i32_e32 v29, 31, v28
	v_lshlrev_b64 v[28:29], 11, v[28:29]
	v_lshl_add_u64 v[28:29], v[20:21], 0, v[28:29]
	global_store_dword v[28:29], v16, off
	ds_read2_b32 v[28:29], v25 offset0:16 offset1:24
	ds_read2_b32 v[30:31], v25 offset0:81 offset1:89
	v_add_u32_e32 v34, 16, v32
	v_ashrrev_i32_e32 v35, 31, v34
	v_lshlrev_b64 v[34:35], 11, v[34:35]
	v_lshl_add_u64 v[34:35], v[20:21], 0, v[34:35]
	s_waitcnt lgkmcnt(0)
	v_cvt_pk_bf16_f32 v16, v28, v30
	v_add_u32_e32 v28, 24, v32
	global_store_dword v[34:35], v16, off
	v_cvt_pk_bf16_f32 v16, v29, v31
	v_ashrrev_i32_e32 v29, 31, v28
	v_lshlrev_b64 v[28:29], 11, v[28:29]
	v_lshl_add_u64 v[28:29], v[20:21], 0, v[28:29]
	global_store_dword v[28:29], v16, off
	ds_read2_b32 v[28:29], v25 offset0:32 offset1:40
	ds_read2_b32 v[30:31], v25 offset0:97 offset1:105
	v_add_u32_e32 v34, 32, v32
	v_ashrrev_i32_e32 v35, 31, v34
	v_lshlrev_b64 v[34:35], 11, v[34:35]
	v_lshl_add_u64 v[34:35], v[20:21], 0, v[34:35]
	s_waitcnt lgkmcnt(0)
	v_cvt_pk_bf16_f32 v16, v28, v30
	v_add_u32_e32 v28, 40, v32
	global_store_dword v[34:35], v16, off
	v_cvt_pk_bf16_f32 v16, v29, v31
	v_ashrrev_i32_e32 v29, 31, v28
	v_lshlrev_b64 v[28:29], 11, v[28:29]
	v_lshl_add_u64 v[28:29], v[20:21], 0, v[28:29]
	global_store_dword v[28:29], v16, off
	ds_read2_b32 v[28:29], v25 offset0:113 offset1:121
	ds_read2_b32 v[30:31], v25 offset0:48 offset1:56
	v_add_u32_e32 v34, 48, v32
	v_ashrrev_i32_e32 v35, 31, v34
	v_lshlrev_b64 v[34:35], 11, v[34:35]
	v_lshl_add_u64 v[34:35], v[20:21], 0, v[34:35]
	s_waitcnt lgkmcnt(0)
	v_cvt_pk_bf16_f32 v16, v30, v28
	v_add_u32_e32 v28, 56, v32
	global_store_dword v[34:35], v16, off
	v_cvt_pk_bf16_f32 v16, v31, v29
	v_ashrrev_i32_e32 v29, 31, v28
	v_lshlrev_b64 v[28:29], 11, v[28:29]
	v_lshl_add_u64 v[20:21], v[20:21], 0, v[28:29]
	s_add_i32 s11, s11, s2
	s_andn2_b64 vcc, exec, s[22:23]
	s_mov_b32 s25, s24
	global_store_dword v[20:21], v16, off
	s_barrier
	s_cbranch_vccz .LBB0_829
	.p2align	6

; __device__ __forceinline__ float ldnt(const float* p) { return __builtin_nontemporal_load(p); }
; __device__ __forceinline__ void conv_job(const float* __restrict__ src, int ld, int K, bf16_t* dst, int Ndst, int kind, float* tile) {
;     ...
;         const int tk = t % tilesK, tn = t / tilesK, k0 = tk << 6, n0 = tn << 6;
; #pragma unroll
;         for (int i = 0; i < 16; ++i) tile[(ty + 4 * i) * 65 + tx] = r[i];
;         __syncthreads();
;         const int tnext = t + gridDim.x;
;         if (tnext < ntiles) {
;             const int tk2 = tnext % tilesK, tn2 = tnext / tilesK, k2 = tk2 << 6, n2 = tn2 << 6;
;             const int sc = mapcol(kind, n2 + tx);
; #pragma unroll
;             for (int i = 0; i < 16; ++i) r[i] = sc >= 0 ? ldnt(src + (size_t)(k2 + ty + 4 * i) * ld + sc) : 0.f;
;         }
; #pragma unroll
;         for (int i = 0; i < 8; ++i) {
;             const int nn = ty2 + 8 * i;
;             *(unsigned*)(dst + (size_t)(n0 + nn) * K + k0 + 2 * tx2) = pack2(tile[(2 * tx2) * 65 + nn], tile[(2 * tx2 + 1) * 65 + nn]);
;         }
;         __syncthreads();
.LBB0_865:
	s_ashr_i32 s22, s13, 31
	s_lshr_b32 s22, s22, 27
	s_add_i32 s13, s13, s22
	s_ashr_i32 s13, s13, 5
	ds_read2_b32 v[28:29], v24 offset0:65 offset1:73
	ds_read2_b32 v[30:31], v24 offset1:8
	s_lshl_b32 s22, s13, 11
	s_sub_i32 s22, s11, s22
	v_lshl_add_u32 v32, s13, 6, v23
	s_ashr_i32 s23, s22, 31
	v_ashrrev_i32_e32 v33, 31, v32
	v_lshl_add_u64 v[20:21], s[22:23], 1, v[18:19]
	v_lshlrev_b64 v[34:35], 12, v[32:33]
	s_waitcnt lgkmcnt(0)
	v_cvt_pk_bf16_f32 v16, v30, v28
	v_lshl_add_u64 v[34:35], v[20:21], 0, v[34:35]
	v_add_u32_e32 v28, 8, v32
	global_store_dword v[34:35], v16, off
	v_cvt_pk_bf16_f32 v16, v31, v29
	v_ashrrev_i32_e32 v29, 31, v28
	v_lshlrev_b64 v[28:29], 12, v[28:29]
	v_lshl_add_u64 v[28:29], v[20:21], 0, v[28:29]
	global_store_dword v[28:29], v16, off
	ds_read2_b32 v[28:29], v24 offset0:16 offset1:24
	ds_read2_b32 v[30:31], v24 offset0:81 offset1:89
	v_add_u32_e32 v34, 16, v32
	v_ashrrev_i32_e32 v35, 31, v34
	v_lshlrev_b64 v[34:35], 12, v[34:35]
	v_lshl_add_u64 v[34:35], v[20:21], 0, v[34:35]
	s_waitcnt lgkmcnt(0)
	v_cvt_pk_bf16_f32 v16, v28, v30
	v_add_u32_e32 v28, 24, v32
	global_store_dword v[34:35], v16, off
	v_cvt_pk_bf16_f32 v16, v29, v31
	v_ashrrev_i32_e32 v29, 31, v28
	v_lshlrev_b64 v[28:29], 12, v[28:29]
	v_lshl_add_u64 v[28:29], v[20:21], 0, v[28:29]
	global_store_dword v[28:29], v16, off
	ds_read2_b32 v[28:29], v24 offset0:32 offset1:40
	ds_read2_b32 v[30:31], v24 offset0:97 offset1:105
	v_add_u32_e32 v34, 32, v32
	v_ashrrev_i32_e32 v35, 31, v34
	v_lshlrev_b64 v[34:35], 12, v[34:35]
	v_lshl_add_u64 v[34:35], v[20:21], 0, v[34:35]
	s_waitcnt lgkmcnt(0)
	v_cvt_pk_bf16_f32 v16, v28, v30
	v_add_u32_e32 v28, 40, v32
	global_store_dword v[34:35], v16, off
	v_cvt_pk_bf16_f32 v16, v29, v31
	v_ashrrev_i32_e32 v29, 31, v28
	v_lshlrev_b64 v[28:29], 12, v[28:29]
	v_lshl_add_u64 v[28:29], v[20:21], 0, v[28:29]
	global_store_dword v[28:29], v16, off
	ds_read2_b32 v[28:29], v24 offset0:113 offset1:121
	ds_read2_b32 v[30:31], v24 offset0:48 offset1:56
	v_add_u32_e32 v34, 48, v32
	v_ashrrev_i32_e32 v35, 31, v34
	v_lshlrev_b64 v[34:35], 12, v[34:35]
	v_lshl_add_u64 v[34:35], v[20:21], 0, v[34:35]
	s_waitcnt lgkmcnt(0)
	v_cvt_pk_bf16_f32 v16, v30, v28
	v_add_u32_e32 v28, 56, v32
	global_store_dword v[34:35], v16, off
	v_cvt_pk_bf16_f32 v16, v31, v29
	v_ashrrev_i32_e32 v29, 31, v28
	v_lshlrev_b64 v[28:29], 12, v[28:29]
	v_lshl_add_u64 v[20:21], v[20:21], 0, v[28:29]
	s_add_i32 s11, s11, s2
	s_andn2_b64 vcc, exec, s[18:19]
	s_mov_b32 s13, s12
	global_store_dword v[20:21], v16, off
	s_barrier
	s_cbranch_vccz .LBB0_899
	.p2align	6

; __device__ __forceinline__ float ldnt(const float* p) { return __builtin_nontemporal_load(p); }
; __device__ __forceinline__ void conv_job(const float* __restrict__ src, int ld, int K, bf16_t* dst, int Ndst, int kind, float* tile) {
;     ...
;         const int tk = t % tilesK, tn = t / tilesK, k0 = tk << 6, n0 = tn << 6;
; #pragma unroll
;         for (int i = 0; i < 16; ++i) tile[(ty + 4 * i) * 65 + tx] = r[i];
;         __syncthreads();
;         const int tnext = t + gridDim.x;
;         if (tnext < ntiles) {
;             const int tk2 = tnext % tilesK, tn2 = tnext / tilesK, k2 = tk2 << 6, n2 = tn2 << 6;
;             const int sc = mapcol(kind, n2 + tx);
; #pragma unroll
;             for (int i = 0; i < 16; ++i) r[i] = sc >= 0 ? ldnt(src + (size_t)(k2 + ty + 4 * i) * ld + sc) : 0.f;
;         }
; #pragma unroll
;         for (int i = 0; i < 8; ++i) {
;             const int nn = ty2 + 8 * i;
;             *(unsigned*)(dst + (size_t)(n0 + nn) * K + k0 + 2 * tx2) = pack2(tile[(2 * tx2) * 65 + nn], tile[(2 * tx2 + 1) * 65 + nn]);
;         }
;         __syncthreads();
.LBB0_942:
	s_ashr_i32 s12, s25, 31
	s_lshr_b32 s12, s12, 28
	s_add_i32 s12, s25, s12
	s_ashr_i32 s22, s12, 4
	ds_read2_b32 v[26:27], v23 offset0:65 offset1:73
	ds_read2_b32 v[28:29], v23 offset1:8
	s_lshl_b32 s12, s22, 10
	s_sub_i32 s12, s11, s12
	v_lshl_add_u32 v30, s22, 6, v22
	s_ashr_i32 s13, s12, 31
	v_ashrrev_i32_e32 v31, 31, v30
	v_lshl_add_u64 v[20:21], s[12:13], 1, v[18:19]
	v_lshlrev_b64 v[32:33], 11, v[30:31]
	s_waitcnt lgkmcnt(0)
	v_cvt_pk_bf16_f32 v26, v28, v26
	v_lshl_add_u64 v[32:33], v[20:21], 0, v[32:33]
	global_store_dword v[32:33], v26, off
	v_add_u32_e32 v26, 8, v30
	v_cvt_pk_bf16_f32 v28, v29, v27
	v_ashrrev_i32_e32 v27, 31, v26
	v_lshlrev_b64 v[26:27], 11, v[26:27]
	v_lshl_add_u64 v[26:27], v[20:21], 0, v[26:27]
	global_store_dword v[26:27], v28, off
	ds_read2_b32 v[26:27], v23 offset0:16 offset1:24
	ds_read2_b32 v[28:29], v23 offset0:81 offset1:89
	v_add_u32_e32 v32, 16, v30
	v_ashrrev_i32_e32 v33, 31, v32
	v_lshlrev_b64 v[32:33], 11, v[32:33]
	v_lshl_add_u64 v[32:33], v[20:21], 0, v[32:33]
	s_waitcnt lgkmcnt(0)
	v_cvt_pk_bf16_f32 v26, v26, v28
	global_store_dword v[32:33], v26, off
	v_add_u32_e32 v26, 24, v30
	v_cvt_pk_bf16_f32 v28, v27, v29
	v_ashrrev_i32_e32 v27, 31, v26
	v_lshlrev_b64 v[26:27], 11, v[26:27]
	v_lshl_add_u64 v[26:27], v[20:21], 0, v[26:27]
	global_store_dword v[26:27], v28, off
	ds_read2_b32 v[26:27], v23 offset0:32 offset1:40
	ds_read2_b32 v[28:29], v23 offset0:97 offset1:105
	v_add_u32_e32 v32, 32, v30
	v_ashrrev_i32_e32 v33, 31, v32
	v_lshlrev_b64 v[32:33], 11, v[32:33]
	v_lshl_add_u64 v[32:33], v[20:21], 0, v[32:33]
	s_waitcnt lgkmcnt(0)
	v_cvt_pk_bf16_f32 v26, v26, v28
	global_store_dword v[32:33], v26, off
	v_add_u32_e32 v26, 40, v30
	v_cvt_pk_bf16_f32 v28, v27, v29
	v_ashrrev_i32_e32 v27, 31, v26
	v_lshlrev_b64 v[26:27], 11, v[26:27]
	v_lshl_add_u64 v[26:27], v[20:21], 0, v[26:27]
	global_store_dword v[26:27], v28, off
	ds_read2_b32 v[26:27], v23 offset0:113 offset1:121
	ds_read2_b32 v[28:29], v23 offset0:48 offset1:56
	v_add_u32_e32 v32, 48, v30
	v_ashrrev_i32_e32 v33, 31, v32
	v_lshlrev_b64 v[32:33], 11, v[32:33]
	v_lshl_add_u64 v[32:33], v[20:21], 0, v[32:33]
	s_waitcnt lgkmcnt(0)
	v_cvt_pk_bf16_f32 v26, v28, v26
	global_store_dword v[32:33], v26, off
	v_add_u32_e32 v26, 56, v30
	v_cvt_pk_bf16_f32 v28, v29, v27
	v_ashrrev_i32_e32 v27, 31, v26
	v_lshlrev_b64 v[26:27], 11, v[26:27]
	v_lshl_add_u64 v[20:21], v[20:21], 0, v[26:27]
	s_add_i32 s11, s11, s2
	s_andn2_b64 vcc, exec, s[18:19]
	s_mov_b32 s25, s24
	global_store_dword v[20:21], v28, off
	s_barrier
	s_cbranch_vccz .LBB0_982
	.p2align	6

; __device__ __forceinline__ float ldnt(const float* p) { return __builtin_nontemporal_load(p); }
; __device__ __forceinline__ void conv_job(const float* __restrict__ src, int ld, int K, bf16_t* dst, int Ndst, int kind, float* tile) {
;     ...
;         const int tk = t % tilesK, tn = t / tilesK, k0 = tk << 6, n0 = tn << 6;
; #pragma unroll
;         for (int i = 0; i < 16; ++i) tile[(ty + 4 * i) * 65 + tx] = r[i];
;         __syncthreads();
;         const int tnext = t + gridDim.x;
;         if (tnext < ntiles) {
;             const int tk2 = tnext % tilesK, tn2 = tnext / tilesK, k2 = tk2 << 6, n2 = tn2 << 6;
;             const int sc = mapcol(kind, n2 + tx);
; #pragma unroll
;             for (int i = 0; i < 16; ++i) r[i] = sc >= 0 ? ldnt(src + (size_t)(k2 + ty + 4 * i) * ld + sc) : 0.f;
;         }
; #pragma unroll
;         for (int i = 0; i < 8; ++i) {
;             const int nn = ty2 + 8 * i;
;             *(unsigned*)(dst + (size_t)(n0 + nn) * K + k0 + 2 * tx2) = pack2(tile[(2 * tx2) * 65 + nn], tile[(2 * tx2 + 1) * 65 + nn]);
;         }
;         __syncthreads();
.LBB0_1019:
	s_ashr_i32 s12, s23, 31
	s_lshr_b32 s12, s12, 28
	s_add_i32 s12, s23, s12
	s_ashr_i32 s23, s12, 4
	ds_read2_b32 v[26:27], v23 offset0:65 offset1:73
	ds_read2_b32 v[28:29], v23 offset1:8
	s_lshl_b32 s12, s23, 10
	s_sub_i32 s12, s11, s12
	v_lshl_add_u32 v30, s23, 6, v22
	s_ashr_i32 s13, s12, 31
	v_ashrrev_i32_e32 v31, 31, v30
	v_lshl_add_u64 v[20:21], s[12:13], 1, v[18:19]
	v_lshlrev_b64 v[32:33], 11, v[30:31]
	s_waitcnt lgkmcnt(0)
	v_cvt_pk_bf16_f32 v26, v28, v26
	v_lshl_add_u64 v[32:33], v[20:21], 0, v[32:33]
	global_store_dword v[32:33], v26, off
	v_add_u32_e32 v26, 8, v30
	v_cvt_pk_bf16_f32 v28, v29, v27
	v_ashrrev_i32_e32 v27, 31, v26
	v_lshlrev_b64 v[26:27], 11, v[26:27]
	v_lshl_add_u64 v[26:27], v[20:21], 0, v[26:27]
	global_store_dword v[26:27], v28, off
	ds_read2_b32 v[26:27], v23 offset0:16 offset1:24
	ds_read2_b32 v[28:29], v23 offset0:81 offset1:89
	v_add_u32_e32 v32, 16, v30
	v_ashrrev_i32_e32 v33, 31, v32
	v_lshlrev_b64 v[32:33], 11, v[32:33]
	v_lshl_add_u64 v[32:33], v[20:21], 0, v[32:33]
	s_waitcnt lgkmcnt(0)
	v_cvt_pk_bf16_f32 v26, v26, v28
	global_store_dword v[32:33], v26, off
	v_add_u32_e32 v26, 24, v30
	v_cvt_pk_bf16_f32 v28, v27, v29
	v_ashrrev_i32_e32 v27, 31, v26
	v_lshlrev_b64 v[26:27], 11, v[26:27]
	v_lshl_add_u64 v[26:27], v[20:21], 0, v[26:27]
	global_store_dword v[26:27], v28, off
	ds_read2_b32 v[26:27], v23 offset0:32 offset1:40
	ds_read2_b32 v[28:29], v23 offset0:97 offset1:105
	v_add_u32_e32 v32, 32, v30
	v_ashrrev_i32_e32 v33, 31, v32
	v_lshlrev_b64 v[32:33], 11, v[32:33]
	v_lshl_add_u64 v[32:33], v[20:21], 0, v[32:33]
	s_waitcnt lgkmcnt(0)
	v_cvt_pk_bf16_f32 v26, v26, v28
	global_store_dword v[32:33], v26, off
	v_add_u32_e32 v26, 40, v30
	v_cvt_pk_bf16_f32 v28, v27, v29
	v_ashrrev_i32_e32 v27, 31, v26
	v_lshlrev_b64 v[26:27], 11, v[26:27]
	v_lshl_add_u64 v[26:27], v[20:21], 0, v[26:27]
	global_store_dword v[26:27], v28, off
	ds_read2_b32 v[26:27], v23 offset0:113 offset1:121
	ds_read2_b32 v[28:29], v23 offset0:48 offset1:56
	v_add_u32_e32 v32, 48, v30
	v_ashrrev_i32_e32 v33, 31, v32
	v_lshlrev_b64 v[32:33], 11, v[32:33]
	v_lshl_add_u64 v[32:33], v[20:21], 0, v[32:33]
	s_waitcnt lgkmcnt(0)
	v_cvt_pk_bf16_f32 v26, v28, v26
	global_store_dword v[32:33], v26, off
	v_add_u32_e32 v26, 56, v30
	v_cvt_pk_bf16_f32 v28, v29, v27
	v_ashrrev_i32_e32 v27, 31, v26
	v_lshlrev_b64 v[26:27], 11, v[26:27]
	v_lshl_add_u64 v[20:21], v[20:21], 0, v[26:27]
	s_add_i32 s11, s11, s2
	s_andn2_b64 vcc, exec, s[18:19]
	s_mov_b32 s23, s22
	global_store_dword v[20:21], v28, off
	s_barrier
	s_cbranch_vccz .LBB0_1053
	.p2align	6

; __device__ __forceinline__ float ldnt(const float* p) { return __builtin_nontemporal_load(p); }
; __device__ __forceinline__ void conv_job(const float* __restrict__ src, int ld, int K, bf16_t* dst, int Ndst, int kind, float* tile) {
;     ...
;         const int tk = t % tilesK, tn = t / tilesK, k0 = tk << 6, n0 = tn << 6;
; #pragma unroll
;         for (int i = 0; i < 16; ++i) tile[(ty + 4 * i) * 65 + tx] = r[i];
;         __syncthreads();
;         const int tnext = t + gridDim.x;
;         if (tnext < ntiles) {
;             const int tk2 = tnext % tilesK, tn2 = tnext / tilesK, k2 = tk2 << 6, n2 = tn2 << 6;
;             const int sc = mapcol(kind, n2 + tx);
; #pragma unroll
;             for (int i = 0; i < 16; ++i) r[i] = sc >= 0 ? ldnt(src + (size_t)(k2 + ty + 4 * i) * ld + sc) : 0.f;
;         }
; #pragma unroll
;         for (int i = 0; i < 8; ++i) {
;             const int nn = ty2 + 8 * i;
;             *(unsigned*)(dst + (size_t)(n0 + nn) * K + k0 + 2 * tx2) = pack2(tile[(2 * tx2) * 65 + nn], tile[(2 * tx2 + 1) * 65 + nn]);
;         }
;         __syncthreads();
.LBB0_1089:
	s_mul_hi_i32 s22, s13, 0x92492493
	s_add_i32 s22, s22, s13
	s_lshr_b32 s13, s22, 31
	s_ashr_i32 s22, s22, 4
	s_add_i32 s13, s22, s13
	ds_read2_b32 v[28:29], v24 offset0:65 offset1:73
	ds_read2_b32 v[30:31], v24 offset1:8
	s_mul_i32 s22, s13, 0xfffff900
	s_add_i32 s22, s11, s22
	s_ashr_i32 s23, s22, 31
	v_lshl_add_u64 v[20:21], s[22:23], 1, v[18:19]
	v_lshl_add_u32 v27, s13, 6, v23
	s_waitcnt lgkmcnt(0)
	v_cvt_pk_bf16_f32 v16, v30, v28
	v_mad_i64_i32 v[32:33], s[22:23], v27, s36, v[20:21]
	v_add_u32_e32 v28, 8, v27
	global_store_dword v[32:33], v16, off
	v_cvt_pk_bf16_f32 v16, v31, v29
	v_mad_i64_i32 v[28:29], s[22:23], v28, s36, v[20:21]
	global_store_dword v[28:29], v16, off
	ds_read2_b32 v[28:29], v24 offset0:16 offset1:24
	ds_read2_b32 v[30:31], v24 offset0:81 offset1:89
	s_add_i32 s11, s11, s2
	s_andn2_b64 vcc, exec, s[18:19]
	s_mov_b32 s13, s12
	s_waitcnt lgkmcnt(0)
	v_cvt_pk_bf16_f32 v16, v28, v30
	v_add_u32_e32 v28, 16, v27
	v_mad_i64_i32 v[32:33], s[22:23], v28, s36, v[20:21]
	v_add_u32_e32 v28, 24, v27
	global_store_dword v[32:33], v16, off
	v_cvt_pk_bf16_f32 v16, v29, v31
	v_mad_i64_i32 v[28:29], s[22:23], v28, s36, v[20:21]
	global_store_dword v[28:29], v16, off
	ds_read2_b32 v[28:29], v24 offset0:32 offset1:40
	ds_read2_b32 v[30:31], v24 offset0:97 offset1:105
	s_waitcnt lgkmcnt(0)
	v_cvt_pk_bf16_f32 v16, v28, v30
	v_add_u32_e32 v28, 32, v27
	v_mad_i64_i32 v[32:33], s[22:23], v28, s36, v[20:21]
	v_add_u32_e32 v28, 40, v27
	global_store_dword v[32:33], v16, off
	v_cvt_pk_bf16_f32 v16, v29, v31
	v_mad_i64_i32 v[28:29], s[22:23], v28, s36, v[20:21]
	global_store_dword v[28:29], v16, off
	ds_read2_b32 v[28:29], v24 offset0:113 offset1:121
	ds_read2_b32 v[30:31], v24 offset0:48 offset1:56
	s_waitcnt lgkmcnt(0)
	v_cvt_pk_bf16_f32 v16, v30, v28
	v_add_u32_e32 v28, 48, v27
	v_mad_i64_i32 v[32:33], s[22:23], v28, s36, v[20:21]
	v_add_u32_e32 v27, 56, v27
	global_store_dword v[32:33], v16, off
	v_cvt_pk_bf16_f32 v16, v31, v29
	v_mad_i64_i32 v[20:21], s[22:23], v27, s36, v[20:21]
	global_store_dword v[20:21], v16, off
	s_barrier
	s_cbranch_vccz .LBB0_1123
	.p2align	6

; __device__ __forceinline__ float ldnt(const float* p) { return __builtin_nontemporal_load(p); }
; __device__ __forceinline__ void conv_job(const float* __restrict__ src, int ld, int K, bf16_t* dst, int Ndst, int kind, float* tile) {
;     ...
;         const int tk = t % tilesK, tn = t / tilesK, k0 = tk << 6, n0 = tn << 6;
; #pragma unroll
;         for (int i = 0; i < 16; ++i) tile[(ty + 4 * i) * 65 + tx] = r[i];
;         __syncthreads();
;         const int tnext = t + gridDim.x;
;         if (tnext < ntiles) {
;             const int tk2 = tnext % tilesK, tn2 = tnext / tilesK, k2 = tk2 << 6, n2 = tn2 << 6;
;             const int sc = mapcol(kind, n2 + tx);
; #pragma unroll
;             for (int i = 0; i < 16; ++i) r[i] = sc >= 0 ? ldnt(src + (size_t)(k2 + ty + 4 * i) * ld + sc) : 0.f;
;         }
; #pragma unroll
;         for (int i = 0; i < 8; ++i) {
;             const int nn = ty2 + 8 * i;
;             *(unsigned*)(dst + (size_t)(n0 + nn) * K + k0 + 2 * tx2) = pack2(tile[(2 * tx2) * 65 + nn], tile[(2 * tx2 + 1) * 65 + nn]);
;         }
;         __syncthreads();
.LBB0_1159:
	s_ashr_i32 s22, s13, 31
	s_lshr_b32 s22, s22, 28
	s_add_i32 s13, s13, s22
	s_ashr_i32 s13, s13, 4
	ds_read2_b32 v[28:29], v24 offset0:65 offset1:73
	ds_read2_b32 v[30:31], v24 offset1:8
	s_lshl_b32 s22, s13, 10
	s_sub_i32 s22, s11, s22
	v_lshl_add_u32 v32, s13, 6, v23
	s_ashr_i32 s23, s22, 31
	v_ashrrev_i32_e32 v33, 31, v32
	v_lshl_add_u64 v[20:21], s[22:23], 1, v[18:19]
	v_lshlrev_b64 v[34:35], 11, v[32:33]
	s_waitcnt lgkmcnt(0)
	v_cvt_pk_bf16_f32 v16, v30, v28
	v_lshl_add_u64 v[34:35], v[20:21], 0, v[34:35]
	v_add_u32_e32 v28, 8, v32
	global_store_dword v[34:35], v16, off
	v_cvt_pk_bf16_f32 v16, v31, v29
	v_ashrrev_i32_e32 v29, 31, v28
	v_lshlrev_b64 v[28:29], 11, v[28:29]
	v_lshl_add_u64 v[28:29], v[20:21], 0, v[28:29]
	global_store_dword v[28:29], v16, off
	ds_read2_b32 v[28:29], v24 offset0:16 offset1:24
	ds_read2_b32 v[30:31], v24 offset0:81 offset1:89
	v_add_u32_e32 v34, 16, v32
	v_ashrrev_i32_e32 v35, 31, v34
	v_lshlrev_b64 v[34:35], 11, v[34:35]
	v_lshl_add_u64 v[34:35], v[20:21], 0, v[34:35]
	s_waitcnt lgkmcnt(0)
	v_cvt_pk_bf16_f32 v16, v28, v30
	v_add_u32_e32 v28, 24, v32
	global_store_dword v[34:35], v16, off
	v_cvt_pk_bf16_f32 v16, v29, v31
	v_ashrrev_i32_e32 v29, 31, v28
	v_lshlrev_b64 v[28:29], 11, v[28:29]
	v_lshl_add_u64 v[28:29], v[20:21], 0, v[28:29]
	global_store_dword v[28:29], v16, off
	ds_read2_b32 v[28:29], v24 offset0:32 offset1:40
	ds_read2_b32 v[30:31], v24 offset0:97 offset1:105
	v_add_u32_e32 v34, 32, v32
	v_ashrrev_i32_e32 v35, 31, v34
	v_lshlrev_b64 v[34:35], 11, v[34:35]
	v_lshl_add_u64 v[34:35], v[20:21], 0, v[34:35]
	s_waitcnt lgkmcnt(0)
	v_cvt_pk_bf16_f32 v16, v28, v30
	v_add_u32_e32 v28, 40, v32
	global_store_dword v[34:35], v16, off
	v_cvt_pk_bf16_f32 v16, v29, v31
	v_ashrrev_i32_e32 v29, 31, v28
	v_lshlrev_b64 v[28:29], 11, v[28:29]
	v_lshl_add_u64 v[28:29], v[20:21], 0, v[28:29]
	global_store_dword v[28:29], v16, off
	ds_read2_b32 v[28:29], v24 offset0:113 offset1:121
	ds_read2_b32 v[30:31], v24 offset0:48 offset1:56
	v_add_u32_e32 v34, 48, v32
	v_ashrrev_i32_e32 v35, 31, v34
	v_lshlrev_b64 v[34:35], 11, v[34:35]
	v_lshl_add_u64 v[34:35], v[20:21], 0, v[34:35]
	s_waitcnt lgkmcnt(0)
	v_cvt_pk_bf16_f32 v16, v30, v28
	v_add_u32_e32 v28, 56, v32
	global_store_dword v[34:35], v16, off
	v_cvt_pk_bf16_f32 v16, v31, v29
	v_ashrrev_i32_e32 v29, 31, v28
	v_lshlrev_b64 v[28:29], 11, v[28:29]
	v_lshl_add_u64 v[20:21], v[20:21], 0, v[28:29]
	s_add_i32 s11, s11, s2
	s_andn2_b64 vcc, exec, s[18:19]
	s_mov_b32 s13, s12
	global_store_dword v[20:21], v16, off
	s_barrier
	s_cbranch_vccz .LBB0_1193
	.p2align	6

; __device__ __forceinline__ float ldnt(const float* p) { return __builtin_nontemporal_load(p); }
; __device__ __forceinline__ void conv_job(const float* __restrict__ src, int ld, int K, bf16_t* dst, int Ndst, int kind, float* tile) {
;     ...
;         const int tk = t % tilesK, tn = t / tilesK, k0 = tk << 6, n0 = tn << 6;
; #pragma unroll
;         for (int i = 0; i < 16; ++i) tile[(ty + 4 * i) * 65 + tx] = r[i];
;         __syncthreads();
;         const int tnext = t + gridDim.x;
;         if (tnext < ntiles) {
;             const int tk2 = tnext % tilesK, tn2 = tnext / tilesK, k2 = tk2 << 6, n2 = tn2 << 6;
;             const int sc = mapcol(kind, n2 + tx);
; #pragma unroll
;             for (int i = 0; i < 16; ++i) r[i] = sc >= 0 ? ldnt(src + (size_t)(k2 + ty + 4 * i) * ld + sc) : 0.f;
;         }
; #pragma unroll
;         for (int i = 0; i < 8; ++i) {
;             const int nn = ty2 + 8 * i;
;             *(unsigned*)(dst + (size_t)(n0 + nn) * K + k0 + 2 * tx2) = pack2(tile[(2 * tx2) * 65 + nn], tile[(2 * tx2 + 1) * 65 + nn]);
;         }
;         __syncthreads();
.LBB0_1301:
	ds_read2_b32 v[52:53], v54 offset0:65 offset1:73
	ds_read2_b32 v[58:59], v54 offset1:8
	v_add_u32_e32 v60, s39, v16
	v_ashrrev_i32_e32 v61, 31, v60
	v_lshlrev_b64 v[62:63], 7, v[60:61]
	v_lshl_add_u64 v[62:63], v[18:19], 0, v[62:63]
	s_waitcnt lgkmcnt(0)
	v_cvt_pk_bf16_f32 v52, v58, v52
	global_store_dword v[62:63], v52, off
	v_add_u32_e32 v52, 8, v60
	v_cvt_pk_bf16_f32 v57, v59, v53
	v_ashrrev_i32_e32 v53, 31, v52
	v_lshlrev_b64 v[52:53], 7, v[52:53]
	v_lshl_add_u64 v[52:53], v[18:19], 0, v[52:53]
	global_store_dword v[52:53], v57, off
	ds_read2_b32 v[52:53], v54 offset0:16 offset1:24
	ds_read2_b32 v[58:59], v54 offset0:81 offset1:89
	v_add_u32_e32 v62, 16, v60
	v_ashrrev_i32_e32 v63, 31, v62
	v_lshlrev_b64 v[62:63], 7, v[62:63]
	v_lshl_add_u64 v[62:63], v[18:19], 0, v[62:63]
	s_waitcnt lgkmcnt(0)
	v_cvt_pk_bf16_f32 v52, v52, v58
	global_store_dword v[62:63], v52, off
	v_add_u32_e32 v52, 24, v60
	v_cvt_pk_bf16_f32 v57, v53, v59
	v_ashrrev_i32_e32 v53, 31, v52
	v_lshlrev_b64 v[52:53], 7, v[52:53]
	v_lshl_add_u64 v[52:53], v[18:19], 0, v[52:53]
	global_store_dword v[52:53], v57, off
	ds_read2_b32 v[52:53], v54 offset0:32 offset1:40
	ds_read2_b32 v[58:59], v54 offset0:97 offset1:105
	v_add_u32_e32 v62, 32, v60
	v_ashrrev_i32_e32 v63, 31, v62
	v_lshlrev_b64 v[62:63], 7, v[62:63]
	v_lshl_add_u64 v[62:63], v[18:19], 0, v[62:63]
	s_waitcnt lgkmcnt(0)
	v_cvt_pk_bf16_f32 v52, v52, v58
	global_store_dword v[62:63], v52, off
	v_add_u32_e32 v52, 40, v60
	v_cvt_pk_bf16_f32 v57, v53, v59
	v_ashrrev_i32_e32 v53, 31, v52
	v_lshlrev_b64 v[52:53], 7, v[52:53]
	v_lshl_add_u64 v[52:53], v[18:19], 0, v[52:53]
	global_store_dword v[52:53], v57, off
	ds_read2_b32 v[52:53], v54 offset0:113 offset1:121
	ds_read2_b32 v[58:59], v54 offset0:48 offset1:56
	v_add_u32_e32 v62, 48, v60
	v_ashrrev_i32_e32 v63, 31, v62
	v_lshlrev_b64 v[62:63], 7, v[62:63]
	v_lshl_add_u64 v[62:63], v[18:19], 0, v[62:63]
	s_waitcnt lgkmcnt(0)
	v_cvt_pk_bf16_f32 v52, v58, v52
	global_store_dword v[62:63], v52, off
	v_add_u32_e32 v52, 56, v60
	v_cvt_pk_bf16_f32 v57, v59, v53
	v_ashrrev_i32_e32 v53, 31, v52
	v_lshlrev_b64 v[52:53], 7, v[52:53]
	v_lshl_add_u64 v[52:53], v[18:19], 0, v[52:53]
	s_add_i32 s39, s39, s24
	s_andn2_b64 vcc, exec, s[22:23]
	global_store_dword v[52:53], v57, off
	s_barrier
	s_cbranch_vccz .LBB0_1335
	.p2align	6

; __device__ __forceinline__ float ldnt(const float* p) { return __builtin_nontemporal_load(p); }
; __device__ __forceinline__ void conv_job(const float* __restrict__ src, int ld, int K, bf16_t* dst, int Ndst, int kind, float* tile) {
;     ...
;         const int tk = t % tilesK, tn = t / tilesK, k0 = tk << 6, n0 = tn << 6;
; #pragma unroll
;         for (int i = 0; i < 16; ++i) tile[(ty + 4 * i) * 65 + tx] = r[i];
;         __syncthreads();
;         const int tnext = t + gridDim.x;
;         if (tnext < ntiles) {
;             const int tk2 = tnext % tilesK, tn2 = tnext / tilesK, k2 = tk2 << 6, n2 = tn2 << 6;
;             const int sc = mapcol(kind, n2 + tx);
; #pragma unroll
;             for (int i = 0; i < 16; ++i) r[i] = sc >= 0 ? ldnt(src + (size_t)(k2 + ty + 4 * i) * ld + sc) : 0.f;
;         }
; #pragma unroll
;         for (int i = 0; i < 8; ++i) {
;             const int nn = ty2 + 8 * i;
;             *(unsigned*)(dst + (size_t)(n0 + nn) * K + k0 + 2 * tx2) = pack2(tile[(2 * tx2) * 65 + nn], tile[(2 * tx2 + 1) * 65 + nn]);
;         }
;         __syncthreads();
.LBB0_1371:
	ds_read2_b32 v[52:53], v54 offset0:65 offset1:73
	ds_read2_b32 v[58:59], v54 offset1:8
	v_add_u32_e32 v60, s24, v16
	v_ashrrev_i32_e32 v61, 31, v60
	v_lshlrev_b64 v[62:63], 7, v[60:61]
	v_lshl_add_u64 v[62:63], v[18:19], 0, v[62:63]
	s_waitcnt lgkmcnt(0)
	v_cvt_pk_bf16_f32 v52, v58, v52
	global_store_dword v[62:63], v52, off
	v_add_u32_e32 v52, 8, v60
	v_cvt_pk_bf16_f32 v57, v59, v53
	v_ashrrev_i32_e32 v53, 31, v52
	v_lshlrev_b64 v[52:53], 7, v[52:53]
	v_lshl_add_u64 v[52:53], v[18:19], 0, v[52:53]
	global_store_dword v[52:53], v57, off
	ds_read2_b32 v[52:53], v54 offset0:16 offset1:24
	ds_read2_b32 v[58:59], v54 offset0:81 offset1:89
	v_add_u32_e32 v62, 16, v60
	v_ashrrev_i32_e32 v63, 31, v62
	v_lshlrev_b64 v[62:63], 7, v[62:63]
	v_lshl_add_u64 v[62:63], v[18:19], 0, v[62:63]
	s_waitcnt lgkmcnt(0)
	v_cvt_pk_bf16_f32 v52, v52, v58
	global_store_dword v[62:63], v52, off
	v_add_u32_e32 v52, 24, v60
	v_cvt_pk_bf16_f32 v57, v53, v59
	v_ashrrev_i32_e32 v53, 31, v52
	v_lshlrev_b64 v[52:53], 7, v[52:53]
	v_lshl_add_u64 v[52:53], v[18:19], 0, v[52:53]
	global_store_dword v[52:53], v57, off
	ds_read2_b32 v[52:53], v54 offset0:32 offset1:40
	ds_read2_b32 v[58:59], v54 offset0:97 offset1:105
	v_add_u32_e32 v62, 32, v60
	v_ashrrev_i32_e32 v63, 31, v62
	v_lshlrev_b64 v[62:63], 7, v[62:63]
	v_lshl_add_u64 v[62:63], v[18:19], 0, v[62:63]
	s_waitcnt lgkmcnt(0)
	v_cvt_pk_bf16_f32 v52, v52, v58
	global_store_dword v[62:63], v52, off
	v_add_u32_e32 v52, 40, v60
	v_cvt_pk_bf16_f32 v57, v53, v59
	v_ashrrev_i32_e32 v53, 31, v52
	v_lshlrev_b64 v[52:53], 7, v[52:53]
	v_lshl_add_u64 v[52:53], v[18:19], 0, v[52:53]
	global_store_dword v[52:53], v57, off
	ds_read2_b32 v[52:53], v54 offset0:113 offset1:121
	ds_read2_b32 v[58:59], v54 offset0:48 offset1:56
	v_add_u32_e32 v62, 48, v60
	v_ashrrev_i32_e32 v63, 31, v62
	v_lshlrev_b64 v[62:63], 7, v[62:63]
	v_lshl_add_u64 v[62:63], v[18:19], 0, v[62:63]
	s_waitcnt lgkmcnt(0)
	v_cvt_pk_bf16_f32 v52, v58, v52
	global_store_dword v[62:63], v52, off
	v_add_u32_e32 v52, 56, v60
	v_cvt_pk_bf16_f32 v57, v59, v53
	v_ashrrev_i32_e32 v53, 31, v52
	v_lshlrev_b64 v[52:53], 7, v[52:53]
	v_lshl_add_u64 v[52:53], v[18:19], 0, v[52:53]
	s_add_i32 s24, s24, s22
	s_andn2_b64 vcc, exec, s[18:19]
	global_store_dword v[52:53], v57, off
	s_barrier
	s_cbranch_vccz .LBB0_1405
	.p2align	6

; __device__ __forceinline__ float ldnt(const float* p) { return __builtin_nontemporal_load(p); }
; __device__ __forceinline__ void conv_job(const float* __restrict__ src, int ld, int K, bf16_t* dst, int Ndst, int kind, float* tile) {
;     ...
;         const int tk = t % tilesK, tn = t / tilesK, k0 = tk << 6, n0 = tn << 6;
; #pragma unroll
;         for (int i = 0; i < 16; ++i) tile[(ty + 4 * i) * 65 + tx] = r[i];
;         __syncthreads();
;         const int tnext = t + gridDim.x;
;         if (tnext < ntiles) {
;             const int tk2 = tnext % tilesK, tn2 = tnext / tilesK, k2 = tk2 << 6, n2 = tn2 << 6;
;             const int sc = mapcol(kind, n2 + tx);
; #pragma unroll
;             for (int i = 0; i < 16; ++i) r[i] = sc >= 0 ? ldnt(src + (size_t)(k2 + ty + 4 * i) * ld + sc) : 0.f;
;         }
; #pragma unroll
;         for (int i = 0; i < 8; ++i) {
;             const int nn = ty2 + 8 * i;
;             *(unsigned*)(dst + (size_t)(n0 + nn) * K + k0 + 2 * tx2) = pack2(tile[(2 * tx2) * 65 + nn], tile[(2 * tx2 + 1) * 65 + nn]);
;         }
;         __syncthreads();
.LBB0_1441:
	s_lshr_b32 s18, s22, 31
	s_add_i32 s18, s22, s18
	s_ashr_i32 s22, s18, 1
	ds_read2_b32 v[28:29], v24 offset0:65 offset1:73
	ds_read2_b32 v[30:31], v24 offset1:8
	s_lshl_b32 s18, s22, 7
	s_sub_i32 s18, s12, s18
	v_lshl_add_u32 v32, s22, 6, v23
	s_ashr_i32 s19, s18, 31
	v_ashrrev_i32_e32 v33, 31, v32
	v_lshl_add_u64 v[20:21], s[18:19], 1, v[18:19]
	v_lshlrev_b64 v[34:35], 8, v[32:33]
	s_waitcnt lgkmcnt(0)
	v_cvt_pk_bf16_f32 v16, v30, v28
	v_lshl_add_u64 v[34:35], v[20:21], 0, v[34:35]
	v_add_u32_e32 v28, 8, v32
	global_store_dword v[34:35], v16, off
	v_cvt_pk_bf16_f32 v16, v31, v29
	v_ashrrev_i32_e32 v29, 31, v28
	v_lshlrev_b64 v[28:29], 8, v[28:29]
	v_lshl_add_u64 v[28:29], v[20:21], 0, v[28:29]
	global_store_dword v[28:29], v16, off
	ds_read2_b32 v[28:29], v24 offset0:16 offset1:24
	ds_read2_b32 v[30:31], v24 offset0:81 offset1:89
	v_add_u32_e32 v34, 16, v32
	v_ashrrev_i32_e32 v35, 31, v34
	v_lshlrev_b64 v[34:35], 8, v[34:35]
	v_lshl_add_u64 v[34:35], v[20:21], 0, v[34:35]
	s_waitcnt lgkmcnt(0)
	v_cvt_pk_bf16_f32 v16, v28, v30
	v_add_u32_e32 v28, 24, v32
	global_store_dword v[34:35], v16, off
	v_cvt_pk_bf16_f32 v16, v29, v31
	v_ashrrev_i32_e32 v29, 31, v28
	v_lshlrev_b64 v[28:29], 8, v[28:29]
	v_lshl_add_u64 v[28:29], v[20:21], 0, v[28:29]
	global_store_dword v[28:29], v16, off
	ds_read2_b32 v[28:29], v24 offset0:32 offset1:40
	ds_read2_b32 v[30:31], v24 offset0:97 offset1:105
	v_add_u32_e32 v34, 32, v32
	v_ashrrev_i32_e32 v35, 31, v34
	v_lshlrev_b64 v[34:35], 8, v[34:35]
	v_lshl_add_u64 v[34:35], v[20:21], 0, v[34:35]
	s_waitcnt lgkmcnt(0)
	v_cvt_pk_bf16_f32 v16, v28, v30
	v_add_u32_e32 v28, 40, v32
	global_store_dword v[34:35], v16, off
	v_cvt_pk_bf16_f32 v16, v29, v31
	v_ashrrev_i32_e32 v29, 31, v28
	v_lshlrev_b64 v[28:29], 8, v[28:29]
	v_lshl_add_u64 v[28:29], v[20:21], 0, v[28:29]
	global_store_dword v[28:29], v16, off
	ds_read2_b32 v[28:29], v24 offset0:113 offset1:121
	ds_read2_b32 v[30:31], v24 offset0:48 offset1:56
	v_add_u32_e32 v34, 48, v32
	v_ashrrev_i32_e32 v35, 31, v34
	v_lshlrev_b64 v[34:35], 8, v[34:35]
	v_lshl_add_u64 v[34:35], v[20:21], 0, v[34:35]
	s_waitcnt lgkmcnt(0)
	v_cvt_pk_bf16_f32 v16, v30, v28
	v_add_u32_e32 v28, 56, v32
	global_store_dword v[34:35], v16, off
	v_cvt_pk_bf16_f32 v16, v31, v29
	v_ashrrev_i32_e32 v29, 31, v28
	v_lshlrev_b64 v[28:29], 8, v[28:29]
	v_lshl_add_u64 v[20:21], v[20:21], 0, v[28:29]
	s_add_i32 s12, s12, s11
	s_and_b64 vcc, exec, s[16:17]
	v_mov_b32_e32 v66, v208
	s_mov_b32 s22, s13
	global_store_dword v[20:21], v16, off
	s_barrier
	s_cbranch_vccnz .LBB0_1475
	.p2align	6

; __device__ __forceinline__ unsigned xb_ld(unsigned* p)              { return __hip_atomic_load(p, __ATOMIC_RELAXED, __HIP_MEMORY_SCOPE_AGENT); }
; __device__ __forceinline__ unsigned xb_add(unsigned* p, unsigned v) { return __hip_atomic_fetch_add(p, v, __ATOMIC_RELAXED, __HIP_MEMORY_SCOPE_AGENT); }
; #define XB_SPIN(cond, bar) do { unsigned _sp = 0; while (cond) { __builtin_amdgcn_s_sleep(1); \
;     if ((++_sp & 255u) == 0u) { if (xb_ld(&(bar)[XB_TMO])) break; if (_sp > XB_SPIN_CAP) { atomicAdd(&(bar)[XB_TMO], 1u); break; } } } } while (0)
; __device__ __forceinline__ void xcd_barrier_complete(unsigned* bar, unsigned x, unsigned& nloc, unsigned& nx) {
;     ...
;     for (;;) {
;         sum = 0u; cnt = 0u; mine = 0u;
; #pragma unroll
;         for (unsigned j = 0; j < 16; ++j) { const unsigned c = xb_ld(&bar[XB_XCNT(j)]); sum += c; cnt += (c > 0u) ? 1u : 0u; mine = (j == x) ? c : mine; }
;         if (sum == G) break;
;         __builtin_amdgcn_s_sleep(1);
;         if ((++sp & 255u) == 0u) { if (xb_ld(&bar[XB_TMO])) break; if (sp > XB_SPIN_CAP) { atomicAdd(&bar[XB_TMO], 1u); break; } }
;     }
;     nloc = mine > 0u ? mine : 1u; nx = cnt > 0u ? cnt : 1u;
; }
; __device__ __forceinline__ void xcd_barrier(const XcdBarrier& b) {
;     asm volatile("s_waitcnt vmcnt(0)" ::: "memory");
;     __syncthreads();
;     if (threadIdx.x == 0) {
;         unsigned* bar = b.bar;
;         __builtin_amdgcn_s_waitcnt(0);
;         unsigned nloc = b.st[0], nx = b.st[1];
;         if (nloc == 0u) { xcd_barrier_complete(bar, b.x, nloc, nx); b.st[0] = nloc; b.st[1] = nx; }
;         const unsigned old = xb_add(&bar[XB_XSUB(b.x)], 1u);
;         const unsigned gen = old / nloc;
;         if (old + 1u == (gen + 1u) * nloc) {
;             __builtin_amdgcn_fence(__ATOMIC_RELEASE, "agent");
;             asm volatile("s_waitcnt vmcnt(0)" ::: "memory");
;             const unsigned og = xb_add(&bar[XB_TOP], 1u);
;             const unsigned tg = og / nx;
;             if (og + 1u == (tg + 1u) * nx) xb_add(&bar[XB_TOPGEN], 1u);
;             else XB_SPIN(xb_ld(&bar[XB_TOPGEN]) == tg, bar);
;             __builtin_amdgcn_fence(__ATOMIC_ACQUIRE, "agent");
;             xb_add(&bar[XB_XGEN(b.x)], 1u);
;             asm volatile("s_waitcnt vmcnt(0)" ::: "memory");
;         } else {
;             XB_SPIN(xb_ld(&bar[XB_XGEN(b.x)]) == gen, bar);
.LBB0_1749:
	s_and_b64 vcc, exec, s[16:17]
	s_cbranch_vccnz .LBB0_1757
	.p2align	6

; __device__ __forceinline__ unsigned xb_ld(unsigned* p)              { return __hip_atomic_load(p, __ATOMIC_RELAXED, __HIP_MEMORY_SCOPE_AGENT); }
; __device__ __forceinline__ unsigned xb_add(unsigned* p, unsigned v) { return __hip_atomic_fetch_add(p, v, __ATOMIC_RELAXED, __HIP_MEMORY_SCOPE_AGENT); }
; #define XB_SPIN(cond, bar) do { unsigned _sp = 0; while (cond) { __builtin_amdgcn_s_sleep(1); \
;     if ((++_sp & 255u) == 0u) { if (xb_ld(&(bar)[XB_TMO])) break; if (_sp > XB_SPIN_CAP) { atomicAdd(&(bar)[XB_TMO], 1u); break; } } } } while (0)
; __device__ __forceinline__ void xcd_barrier_complete(unsigned* bar, unsigned x, unsigned& nloc, unsigned& nx) {
;     ...
;     for (;;) {
;         sum = 0u; cnt = 0u; mine = 0u;
; #pragma unroll
;         for (unsigned j = 0; j < 16; ++j) { const unsigned c = xb_ld(&bar[XB_XCNT(j)]); sum += c; cnt += (c > 0u) ? 1u : 0u; mine = (j == x) ? c : mine; }
;         if (sum == G) break;
;         __builtin_amdgcn_s_sleep(1);
;         if ((++sp & 255u) == 0u) { if (xb_ld(&bar[XB_TMO])) break; if (sp > XB_SPIN_CAP) { atomicAdd(&bar[XB_TMO], 1u); break; } }
;     }
;     nloc = mine > 0u ? mine : 1u; nx = cnt > 0u ? cnt : 1u;
; }
; __device__ __forceinline__ void xcd_barrier(const XcdBarrier& b) {
;     asm volatile("s_waitcnt vmcnt(0)" ::: "memory");
;     __syncthreads();
;     if (threadIdx.x == 0) {
;         unsigned* bar = b.bar;
;         __builtin_amdgcn_s_waitcnt(0);
;         unsigned nloc = b.st[0], nx = b.st[1];
;         if (nloc == 0u) { xcd_barrier_complete(bar, b.x, nloc, nx); b.st[0] = nloc; b.st[1] = nx; }
;         const unsigned old = xb_add(&bar[XB_XSUB(b.x)], 1u);
;         const unsigned gen = old / nloc;
;         if (old + 1u == (gen + 1u) * nloc) {
;             __builtin_amdgcn_fence(__ATOMIC_RELEASE, "agent");
;             asm volatile("s_waitcnt vmcnt(0)" ::: "memory");
;             const unsigned og = xb_add(&bar[XB_TOP], 1u);
;             const unsigned tg = og / nx;
;             if (og + 1u == (tg + 1u) * nx) xb_add(&bar[XB_TOPGEN], 1u);
;             else XB_SPIN(xb_ld(&bar[XB_TOPGEN]) == tg, bar);
;             __builtin_amdgcn_fence(__ATOMIC_ACQUIRE, "agent");
;             xb_add(&bar[XB_XGEN(b.x)], 1u);
;             asm volatile("s_waitcnt vmcnt(0)" ::: "memory");
;         } else {
;             XB_SPIN(xb_ld(&bar[XB_XGEN(b.x)]) == gen, bar);
.LBB0_1767:
	s_and_b64 s[10:11], exec, s[24:25]
	s_or_b64 s[18:19], s[10:11], s[18:19]
	s_andn2_b64 s[10:11], s[22:23], exec
	s_and_b64 s[12:13], s[40:41], exec
	s_or_b64 s[22:23], s[10:11], s[12:13]
	s_andn2_b64 exec, exec, s[18:19]
	s_cbranch_execz .LBB0_1774
	.p2align	6

; __device__ __forceinline__ unsigned xb_ld(unsigned* p)              { return __hip_atomic_load(p, __ATOMIC_RELAXED, __HIP_MEMORY_SCOPE_AGENT); }
; __device__ __forceinline__ unsigned xb_add(unsigned* p, unsigned v) { return __hip_atomic_fetch_add(p, v, __ATOMIC_RELAXED, __HIP_MEMORY_SCOPE_AGENT); }
; #define XB_SPIN(cond, bar) do { unsigned _sp = 0; while (cond) { __builtin_amdgcn_s_sleep(1); \
;     if ((++_sp & 255u) == 0u) { if (xb_ld(&(bar)[XB_TMO])) break; if (_sp > XB_SPIN_CAP) { atomicAdd(&(bar)[XB_TMO], 1u); break; } } } } while (0)
; __device__ __forceinline__ void xcd_barrier_complete(unsigned* bar, unsigned x, unsigned& nloc, unsigned& nx) {
;     ...
;     for (;;) {
;         sum = 0u; cnt = 0u; mine = 0u;
; #pragma unroll
;         for (unsigned j = 0; j < 16; ++j) { const unsigned c = xb_ld(&bar[XB_XCNT(j)]); sum += c; cnt += (c > 0u) ? 1u : 0u; mine = (j == x) ? c : mine; }
;         if (sum == G) break;
;         __builtin_amdgcn_s_sleep(1);
;         if ((++sp & 255u) == 0u) { if (xb_ld(&bar[XB_TMO])) break; if (sp > XB_SPIN_CAP) { atomicAdd(&bar[XB_TMO], 1u); break; } }
;     }
;     nloc = mine > 0u ? mine : 1u; nx = cnt > 0u ? cnt : 1u;
; }
; __device__ __forceinline__ void xcd_barrier(const XcdBarrier& b) {
;     asm volatile("s_waitcnt vmcnt(0)" ::: "memory");
;     __syncthreads();
;     if (threadIdx.x == 0) {
;         unsigned* bar = b.bar;
;         __builtin_amdgcn_s_waitcnt(0);
;         unsigned nloc = b.st[0], nx = b.st[1];
;         if (nloc == 0u) { xcd_barrier_complete(bar, b.x, nloc, nx); b.st[0] = nloc; b.st[1] = nx; }
;         const unsigned old = xb_add(&bar[XB_XSUB(b.x)], 1u);
;         const unsigned gen = old / nloc;
;         if (old + 1u == (gen + 1u) * nloc) {
;             __builtin_amdgcn_fence(__ATOMIC_RELEASE, "agent");
;             asm volatile("s_waitcnt vmcnt(0)" ::: "memory");
;             const unsigned og = xb_add(&bar[XB_TOP], 1u);
;             const unsigned tg = og / nx;
;             if (og + 1u == (tg + 1u) * nx) xb_add(&bar[XB_TOPGEN], 1u);
;             else XB_SPIN(xb_ld(&bar[XB_TOPGEN]) == tg, bar);
;             __builtin_amdgcn_fence(__ATOMIC_ACQUIRE, "agent");
;             xb_add(&bar[XB_XGEN(b.x)], 1u);
;             asm volatile("s_waitcnt vmcnt(0)" ::: "memory");
;         } else {
;             XB_SPIN(xb_ld(&bar[XB_XGEN(b.x)]) == gen, bar);
.LBB0_1784:
	s_xor_b64 s[10:11], s[40:41], -1
	s_and_b64 s[12:13], exec, s[24:25]
	s_or_b64 s[18:19], s[12:13], s[18:19]
	s_andn2_b64 s[12:13], s[22:23], exec
	s_and_b64 s[10:11], s[10:11], exec
	s_or_b64 s[22:23], s[12:13], s[10:11]
	s_andn2_b64 exec, exec, s[18:19]
	s_cbranch_execz .LBB0_1791
	.p2align	6
